# GEMM accumulator zeroing with v_mov_b64 (64 instead of 128 moves per tile) on top of packed ConvFFN epilogue
# baseline (speedup 1.0000x reference)
;     DEV bool next(int i, Unit& u) const { return tile((long)i * G + c, u); }
;     DEV bool next(int i, Unit& u) const { const int round = i / 3, br = i - round * 3; Unit t; if (!so.tile((long)round * so.G + so.c, t)) return false; u.pm = br * 64 + t.pm; u.pn = br * 4 + t.pn; return true; }
; template <bool ALIGN_EPI, class Epi, class Sched>
; DEV void gemm_phase(LAS unsigned char* lds, const Gemm g, const Sched& S, const Epi& E) {
;     ...
;         const bool has_next = S.next(ui + 1, nxt);
;         const char* nA = has_next ? (const char*)g.A + (size_t)nxt.pm * tstep : cA; const char* nB = has_next ? (const char*)g.Bt + (size_t)nxt.pn * tstep : cB;
;         for (int t = 0; t < nt; t += 2) {
;     ...
;         if (rst) {
; #pragma unroll
;         for (int a = 0; a < 2; ++a)
; #pragma unroll
;             for (int b = 0; b < 2; ++b)
; #pragma unroll
;                 for (int m = 0; m < 4; ++m)
; #pragma unroll
;                     for (int n = 0; n < 2; ++n) acc[a][b][m][n] = (f32x4){0.f, 0.f, 0.f, 0.f}; }
.LBB0_27:
	s_ashr_i32 s85, s84, 31
	s_lshl_b64 s[48:49], s[84:85], 19
	s_add_u32 s86, s34, s48
	s_addc_u32 s87, s35, s49
	s_and_b64 s[48:49], s[44:45], exec
	s_cselect_b32 s85, s87, s5
	s_cselect_b32 vcc_lo, s86, s4
	s_ashr_i32 s83, s82, 31
	s_lshl_b64 s[48:49], s[82:83], 19
	s_add_u32 s88, s38, s48
	s_addc_u32 s89, s39, s49
	s_and_b64 s[48:49], s[44:45], exec
	s_cselect_b32 s83, s89, s7
	s_cselect_b32 vcc_hi, s88, s6
	s_add_u32 s21, s6, 0x100
	v_mov_b32_e32 v2, 0
	s_addc_u32 s48, s7, 0
	s_mov_b32 s49, -2
	v_mov_b32_e32 v3, v2
	v_mov_b64_e32 v[4:5], 0
	v_mov_b64_e32 v[18:19], 0
	v_mov_b64_e32 v[20:21], 0
	v_mov_b64_e32 v[34:35], 0
	v_mov_b64_e32 v[36:37], 0
	v_mov_b64_e32 v[42:43], 0
	v_mov_b64_e32 v[44:45], 0
	v_mov_b64_e32 v[50:51], 0
	v_mov_b64_e32 v[52:53], 0
	v_mov_b64_e32 v[58:59], 0
	v_mov_b64_e32 v[60:61], 0
	v_mov_b64_e32 v[74:75], 0
	v_mov_b64_e32 v[76:77], 0
	v_mov_b64_e32 v[90:91], 0
	v_mov_b64_e32 v[92:93], 0
	v_mov_b64_e32 v[6:7], 0
	v_mov_b64_e32 v[8:9], 0
	v_mov_b64_e32 v[22:23], 0
	v_mov_b64_e32 v[24:25], 0
	v_mov_b64_e32 v[10:11], 0
	v_mov_b64_e32 v[12:13], 0
	v_mov_b64_e32 v[26:27], 0
	v_mov_b64_e32 v[28:29], 0
	v_mov_b64_e32 v[14:15], 0
	v_mov_b64_e32 v[16:17], 0
	v_mov_b64_e32 v[30:31], 0
	v_mov_b64_e32 v[32:33], 0
	v_mov_b64_e32 v[38:39], 0
	v_mov_b64_e32 v[40:41], 0
	v_mov_b64_e32 v[46:47], 0
	v_mov_b64_e32 v[48:49], 0
	v_mov_b64_e32 v[98:99], 0
	v_mov_b64_e32 v[100:101], 0
	v_mov_b64_e32 v[106:107], 0
	v_mov_b64_e32 v[108:109], 0
	v_mov_b64_e32 v[114:115], 0
	v_mov_b64_e32 v[116:117], 0
	v_mov_b64_e32 v[126:127], 0
	v_mov_b64_e32 v[128:129], 0
	v_mov_b64_e32 v[138:139], 0
	v_mov_b64_e32 v[140:141], 0
	v_mov_b64_e32 v[142:143], 0
	v_mov_b64_e32 v[144:145], 0
	v_mov_b64_e32 v[146:147], 0
	v_mov_b64_e32 v[148:149], 0
	v_mov_b64_e32 v[150:151], 0
	v_mov_b64_e32 v[152:153], 0
	v_mov_b64_e32 v[54:55], 0
	v_mov_b64_e32 v[56:57], 0
	v_mov_b64_e32 v[70:71], 0
	v_mov_b64_e32 v[72:73], 0
	v_mov_b64_e32 v[86:87], 0
	v_mov_b64_e32 v[88:89], 0
	v_mov_b64_e32 v[94:95], 0
	v_mov_b64_e32 v[96:97], 0
	v_mov_b64_e32 v[102:103], 0
	v_mov_b64_e32 v[104:105], 0
	v_mov_b64_e32 v[110:111], 0
	v_mov_b64_e32 v[112:113], 0
	v_mov_b64_e32 v[118:119], 0
	v_mov_b64_e32 v[120:121], 0
	v_mov_b64_e32 v[130:131], 0
	v_mov_b64_e32 v[132:133], 0

;     DEV bool next(int i, Unit& u) const { return tile((long)i * G + c, u); }
;     DEV bool next(int i, Unit& u) const { const int round = i / 3, br = i - round * 3; Unit t; if (!so.tile((long)round * so.G + so.c, t)) return false; u.pm = br * 64 + t.pm; u.pn = br * 4 + t.pn; return true; }
; template <bool ALIGN_EPI, class Epi, class Sched>
; DEV void gemm_phase(LAS unsigned char* lds, const Gemm g, const Sched& S, const Epi& E) {
;     ...
;         const bool has_next = S.next(ui + 1, nxt);
;         const char* nA = has_next ? (const char*)g.A + (size_t)nxt.pm * tstep : cA; const char* nB = has_next ? (const char*)g.Bt + (size_t)nxt.pn * tstep : cB;
;         for (int t = 0; t < nt; t += 2) {
;     ...
;         if (rst) {
; #pragma unroll
;         for (int a = 0; a < 2; ++a)
; #pragma unroll
;             for (int b = 0; b < 2; ++b)
; #pragma unroll
;                 for (int m = 0; m < 4; ++m)
; #pragma unroll
;                     for (int n = 0; n < 2; ++n) acc[a][b][m][n] = (f32x4){0.f, 0.f, 0.f, 0.f}; }
.LBB0_68:
	s_ashr_i32 s51, s50, 31
	s_lshl_b64 s[52:53], s[50:51], 19
	s_add_u32 s52, s34, s52
	s_addc_u32 s53, s35, s53
	s_and_b64 s[54:55], s[40:41], exec
	s_cselect_b32 s51, s53, s5
	s_cselect_b32 s81, s52, s4
	s_ashr_i32 s49, s48, 31
	s_lshl_b64 s[54:55], s[48:49], 19
	s_add_u32 s54, s66, s54
	s_addc_u32 s55, s67, s55
	s_and_b64 s[78:79], s[40:41], exec
	s_cselect_b32 s49, s55, s7
	s_cselect_b32 s82, s54, s6
	s_add_u32 s4, s4, 0x40080
	s_addc_u32 s5, s5, 0
	s_add_u32 s83, s6, 0x100
	v_mov_b32_e32 v2, 0
	s_addc_u32 s84, s7, 0
	s_mov_b32 s85, -2
	v_mov_b32_e32 v3, v2
	v_mov_b64_e32 v[4:5], 0
	v_mov_b64_e32 v[6:7], 0
	v_mov_b64_e32 v[8:9], 0
	v_mov_b64_e32 v[14:15], 0
	v_mov_b64_e32 v[16:17], 0
	v_mov_b64_e32 v[22:23], 0
	v_mov_b64_e32 v[24:25], 0
	v_mov_b64_e32 v[30:31], 0
	v_mov_b64_e32 v[32:33], 0
	v_mov_b64_e32 v[38:39], 0
	v_mov_b64_e32 v[40:41], 0
	v_mov_b64_e32 v[46:47], 0
	v_mov_b64_e32 v[48:49], 0
	v_mov_b64_e32 v[54:55], 0
	v_mov_b64_e32 v[56:57], 0
	v_mov_b64_e32 v[10:11], 0
	v_mov_b64_e32 v[12:13], 0
	v_mov_b64_e32 v[18:19], 0
	v_mov_b64_e32 v[20:21], 0
	v_mov_b64_e32 v[26:27], 0
	v_mov_b64_e32 v[28:29], 0
	v_mov_b64_e32 v[34:35], 0
	v_mov_b64_e32 v[36:37], 0
	v_mov_b64_e32 v[42:43], 0
	v_mov_b64_e32 v[44:45], 0
	v_mov_b64_e32 v[50:51], 0
	v_mov_b64_e32 v[52:53], 0
	v_mov_b64_e32 v[58:59], 0
	v_mov_b64_e32 v[60:61], 0
	v_mov_b64_e32 v[62:63], 0
	v_mov_b64_e32 v[64:65], 0
	v_mov_b64_e32 v[66:67], 0
	v_mov_b64_e32 v[68:69], 0
	v_mov_b64_e32 v[70:71], 0
	v_mov_b64_e32 v[72:73], 0
	v_mov_b64_e32 v[78:79], 0
	v_mov_b64_e32 v[80:81], 0
	v_mov_b64_e32 v[86:87], 0
	v_mov_b64_e32 v[88:89], 0
	v_mov_b64_e32 v[94:95], 0
	v_mov_b64_e32 v[96:97], 0
	v_mov_b64_e32 v[102:103], 0
	v_mov_b64_e32 v[104:105], 0
	v_mov_b64_e32 v[114:115], 0
	v_mov_b64_e32 v[116:117], 0
	v_mov_b64_e32 v[118:119], 0
	v_mov_b64_e32 v[120:121], 0
	v_mov_b64_e32 v[74:75], 0
	v_mov_b64_e32 v[76:77], 0
	v_mov_b64_e32 v[82:83], 0
	v_mov_b64_e32 v[84:85], 0
	v_mov_b64_e32 v[90:91], 0
	v_mov_b64_e32 v[92:93], 0
	v_mov_b64_e32 v[98:99], 0
	v_mov_b64_e32 v[100:101], 0
	v_mov_b64_e32 v[106:107], 0
	v_mov_b64_e32 v[108:109], 0
	v_mov_b64_e32 v[110:111], 0
	v_mov_b64_e32 v[112:113], 0
	v_mov_b64_e32 v[122:123], 0
	v_mov_b64_e32 v[124:125], 0
	v_mov_b64_e32 v[126:127], 0
	v_mov_b64_e32 v[128:129], 0

;     DEV bool next(int i, Unit& u) const { return tile((long)i * G + c, u); }
;     DEV bool next(int i, Unit& u) const { const int round = i / 3, br = i - round * 3; Unit t; if (!so.tile((long)round * so.G + so.c, t)) return false; u.pm = br * 64 + t.pm; u.pn = br * 4 + t.pn; return true; }
; template <bool ALIGN_EPI, class Epi, class Sched>
; DEV void gemm_phase(LAS unsigned char* lds, const Gemm g, const Sched& S, const Epi& E) {
;     ...
;         const bool has_next = S.next(ui + 1, nxt);
;         const char* nA = has_next ? (const char*)g.A + (size_t)nxt.pm * tstep : cA; const char* nB = has_next ? (const char*)g.Bt + (size_t)nxt.pn * tstep : cB;
;         for (int t = 0; t < nt; t += 2) {
;     ...
;         if (rst) {
; #pragma unroll
;         for (int a = 0; a < 2; ++a)
; #pragma unroll
;             for (int b = 0; b < 2; ++b)
; #pragma unroll
;                 for (int m = 0; m < 4; ++m)
; #pragma unroll
;                     for (int n = 0; n < 2; ++n) acc[a][b][m][n] = (f32x4){0.f, 0.f, 0.f, 0.f}; }
.LBB0_314:
	s_ashr_i32 s93, s92, 31
	s_lshl_b64 s[46:47], s[92:93], 19
	s_add_u32 s88, s34, s46
	s_addc_u32 s89, s35, s47
	s_and_b64 s[46:47], s[44:45], exec
	s_cselect_b32 s17, s89, s5
	s_cselect_b32 s36, s88, s4
	s_ashr_i32 s85, s84, 31
	s_lshl_b64 s[46:47], s[84:85], 19
	s_add_u32 s90, s62, s46
	s_addc_u32 s91, s63, s47
	s_and_b64 s[46:47], s[44:45], exec
	s_cselect_b32 s41, s91, s7
	s_cselect_b32 s64, s90, s6
	s_add_u32 s70, s6, 0x100
	v_mov_b32_e32 v2, 0
	s_addc_u32 s85, s7, 0
	s_mov_b32 s87, -2
	v_mov_b32_e32 v3, v2
	v_mov_b64_e32 v[4:5], 0
	v_mov_b64_e32 v[6:7], 0
	v_mov_b64_e32 v[8:9], 0
	v_mov_b64_e32 v[18:19], 0
	v_mov_b64_e32 v[20:21], 0
	v_mov_b64_e32 v[22:23], 0
	s_waitcnt vmcnt(0)
	v_mov_b64_e32 v[24:25], 0
	v_mov_b64_e32 v[34:35], 0
	v_mov_b64_e32 v[36:37], 0
	v_mov_b64_e32 v[38:39], 0
	v_mov_b64_e32 v[40:41], 0
	v_mov_b64_e32 v[50:51], 0
	v_mov_b64_e32 v[52:53], 0
	v_mov_b64_e32 v[54:55], 0
	v_mov_b64_e32 v[56:57], 0
	v_mov_b64_e32 v[10:11], 0
	v_mov_b64_e32 v[12:13], 0
	v_mov_b64_e32 v[14:15], 0
	v_mov_b64_e32 v[16:17], 0
	v_mov_b64_e32 v[26:27], 0
	v_mov_b64_e32 v[28:29], 0
	v_mov_b64_e32 v[30:31], 0
	v_mov_b64_e32 v[32:33], 0
	v_mov_b64_e32 v[42:43], 0
	v_mov_b64_e32 v[44:45], 0
	v_mov_b64_e32 v[46:47], 0
	v_mov_b64_e32 v[48:49], 0
	v_mov_b64_e32 v[58:59], 0
	v_mov_b64_e32 v[60:61], 0
	v_mov_b64_e32 v[62:63], 0
	v_mov_b64_e32 v[64:65], 0
	v_mov_b64_e32 v[66:67], 0
	v_mov_b64_e32 v[68:69], 0
	v_mov_b64_e32 v[70:71], 0
	v_mov_b64_e32 v[72:73], 0
	v_mov_b64_e32 v[82:83], 0
	v_mov_b64_e32 v[84:85], 0
	v_mov_b64_e32 v[86:87], 0
	v_mov_b64_e32 v[88:89], 0
	v_mov_b64_e32 v[98:99], 0
	v_mov_b64_e32 v[100:101], 0
	v_mov_b64_e32 v[102:103], 0
	v_mov_b64_e32 v[104:105], 0
	v_mov_b64_e32 v[114:115], 0
	v_mov_b64_e32 v[116:117], 0
	v_mov_b64_e32 v[118:119], 0
	v_mov_b64_e32 v[120:121], 0
	v_mov_b64_e32 v[74:75], 0
	v_mov_b64_e32 v[76:77], 0
	v_mov_b64_e32 v[78:79], 0
	v_mov_b64_e32 v[80:81], 0
	v_mov_b64_e32 v[90:91], 0
	v_mov_b64_e32 v[92:93], 0
	v_mov_b64_e32 v[94:95], 0
	v_mov_b64_e32 v[96:97], 0
	v_mov_b64_e32 v[106:107], 0
	v_mov_b64_e32 v[108:109], 0
	v_mov_b64_e32 v[110:111], 0
	v_mov_b64_e32 v[112:113], 0
	v_mov_b64_e32 v[122:123], 0
	v_mov_b64_e32 v[124:125], 0
	v_mov_b64_e32 v[126:127], 0
	v_mov_b64_e32 v[128:129], 0

; template <bool ALIGN_EPI, class Epi, class Sched>
; DEV void gemm_phase(LAS unsigned char* lds, const Gemm g, const Sched& S, const Epi& E) {
;     ...
;         if (rst) {
; #pragma unroll
;         for (int a = 0; a < 2; ++a)
; #pragma unroll
;             for (int b = 0; b < 2; ++b)
; #pragma unroll
;                 for (int m = 0; m < 4; ++m)
; #pragma unroll
;                     for (int n = 0; n < 2; ++n) acc[a][b][m][n] = (f32x4){0.f, 0.f, 0.f, 0.f}; }
.LBB0_487:
	s_add_u32 s78, s6, 0x100
	v_mov_b32_e32 v2, 0
	s_addc_u32 s79, s7, 0
	s_mov_b32 s80, -2
	v_mov_b32_e32 v3, v2
	v_mov_b64_e32 v[4:5], 0
	v_mov_b64_e32 v[6:7], 0
	v_mov_b64_e32 v[8:9], 0
	v_mov_b64_e32 v[14:15], 0
	v_mov_b64_e32 v[16:17], 0
	v_mov_b64_e32 v[22:23], 0
	v_mov_b64_e32 v[24:25], 0
	v_mov_b64_e32 v[30:31], 0
	v_mov_b64_e32 v[32:33], 0
	v_mov_b64_e32 v[38:39], 0
	v_mov_b64_e32 v[40:41], 0
	v_mov_b64_e32 v[46:47], 0
	v_mov_b64_e32 v[48:49], 0
	v_mov_b64_e32 v[54:55], 0
	v_mov_b64_e32 v[56:57], 0
	v_mov_b64_e32 v[10:11], 0
	v_mov_b64_e32 v[12:13], 0
	v_mov_b64_e32 v[18:19], 0
	v_mov_b64_e32 v[20:21], 0
	v_mov_b64_e32 v[26:27], 0
	v_mov_b64_e32 v[28:29], 0
	v_mov_b64_e32 v[34:35], 0
	v_mov_b64_e32 v[36:37], 0
	v_mov_b64_e32 v[42:43], 0
	v_mov_b64_e32 v[44:45], 0
	v_mov_b64_e32 v[50:51], 0
	v_mov_b64_e32 v[52:53], 0
	v_mov_b64_e32 v[58:59], 0
	v_mov_b64_e32 v[60:61], 0
	v_mov_b64_e32 v[62:63], 0
	v_mov_b64_e32 v[64:65], 0
	v_mov_b64_e32 v[66:67], 0
	v_mov_b64_e32 v[68:69], 0
	v_mov_b64_e32 v[70:71], 0
	v_mov_b64_e32 v[72:73], 0
	v_mov_b64_e32 v[78:79], 0
	v_mov_b64_e32 v[80:81], 0
	v_mov_b64_e32 v[86:87], 0
	v_mov_b64_e32 v[88:89], 0
	v_mov_b64_e32 v[94:95], 0
	v_mov_b64_e32 v[96:97], 0
	v_mov_b64_e32 v[102:103], 0
	v_mov_b64_e32 v[104:105], 0
	v_mov_b64_e32 v[114:115], 0
	v_mov_b64_e32 v[116:117], 0
	v_mov_b64_e32 v[118:119], 0
	v_mov_b64_e32 v[120:121], 0
	v_mov_b64_e32 v[74:75], 0
	v_mov_b64_e32 v[76:77], 0
	v_mov_b64_e32 v[82:83], 0
	v_mov_b64_e32 v[84:85], 0
	v_mov_b64_e32 v[90:91], 0
	v_mov_b64_e32 v[92:93], 0
	v_mov_b64_e32 v[98:99], 0
	v_mov_b64_e32 v[100:101], 0
	v_mov_b64_e32 v[106:107], 0
	v_mov_b64_e32 v[108:109], 0
	v_mov_b64_e32 v[110:111], 0
	v_mov_b64_e32 v[112:113], 0
	v_mov_b64_e32 v[122:123], 0
	v_mov_b64_e32 v[124:125], 0
	v_mov_b64_e32 v[126:127], 0
	v_mov_b64_e32 v[128:129], 0
